# mp0 attention row-sum adds interleaved into final P.V MFMA run
# speedup vs baseline: 1.0198x; 1.0008x over previous
.LBB0_638:
	s_add_i32 s4, s44, 0x9000
	s_cmp_lg_u32 s44, 0x12000
	s_cselect_b32 s44, s4, 0
	s_add_i32 s4, s45, 1
	s_cmp_lg_u32 s45, 2
	s_cselect_b32 s45, s4, 0
	s_add_i32 s33, s33, 1
	s_add_u32 s76, s76, 0x80
	s_addc_u32 s77, s77, 0
	s_add_u32 s10, s10, 0x60000
	s_addc_u32 s11, s11, 0
	s_add_i32 s20, s20, 64
	s_cmpk_eq_i32 s20, 0xfc0
	s_cbranch_scc1 .LBB0_649

.LBB0_645:
	ds_read_b128 v[178:181], v168 offset:27648
	ds_read_b128 v[182:185], v168 offset:27664
	ds_read_b128 v[186:189], v168 offset:32256
	ds_read_b128 v[190:193], v168 offset:32272
	v_exp_f32_e32 v96, v96
	v_exp_f32_e32 v97, v97
	v_exp_f32_e32 v98, v98
	v_exp_f32_e32 v99, v99
	v_exp_f32_e32 v100, v100
	v_exp_f32_e32 v101, v101
	v_exp_f32_e32 v102, v102
	v_exp_f32_e32 v103, v103
	v_exp_f32_e32 v104, v104
	v_exp_f32_e32 v105, v105
	v_exp_f32_e32 v106, v106
	v_exp_f32_e32 v107, v107
	v_exp_f32_e32 v108, v108
	v_exp_f32_e32 v109, v109
	v_exp_f32_e32 v110, v110
	v_exp_f32_e32 v111, v111
	v_cvt_pk_bf16_f32 v170, v96, v97
	v_cvt_pk_bf16_f32 v171, v98, v99
	v_cvt_pk_bf16_f32 v172, v100, v101
	v_cvt_pk_bf16_f32 v173, v102, v103
	v_cvt_pk_bf16_f32 v194, v104, v105
	v_cvt_pk_bf16_f32 v195, v106, v107
	v_cvt_pk_bf16_f32 v196, v108, v109
	v_cvt_pk_bf16_f32 v197, v110, v111
	s_waitcnt lgkmcnt(0)
	v_mfma_f32_32x32x16_bf16 v[48:63], v[140:143], v[170:173], v[48:63]
	v_exp_f32_e32 v80, v80
	v_exp_f32_e32 v81, v81
	v_exp_f32_e32 v82, v82
	v_exp_f32_e32 v83, v83
	v_mfma_f32_32x32x16_bf16 v[0:15], v[136:139], v[170:173], v[0:15]
	v_mfma_f32_32x32x16_bf16 v[48:63], v[132:135], v[194:197], v[48:63]
	v_exp_f32_e32 v84, v84
	v_exp_f32_e32 v85, v85
	v_exp_f32_e32 v86, v86
	v_exp_f32_e32 v87, v87
	v_mfma_f32_32x32x16_bf16 v[0:15], v[128:131], v[194:197], v[0:15]
	ds_read_b128 v[128:131], v168 offset:18496
	ds_read_b128 v[132:135], v168 offset:18512
	ds_read_b128 v[136:139], v168 offset:23104
	ds_read_b128 v[140:143], v168 offset:23120
	v_mfma_f32_32x32x16_bf16 v[32:47], v[178:181], v[170:173], v[32:47]
	v_exp_f32_e32 v88, v88
	v_exp_f32_e32 v89, v89
	v_exp_f32_e32 v90, v90
	v_exp_f32_e32 v91, v91
	v_mfma_f32_32x32x16_bf16 v[16:31], v[186:189], v[170:173], v[16:31]
	v_mfma_f32_32x32x16_bf16 v[32:47], v[182:185], v[194:197], v[32:47]
	v_exp_f32_e32 v92, v92
	v_exp_f32_e32 v93, v93
	v_exp_f32_e32 v94, v94
	v_exp_f32_e32 v95, v95
	v_cvt_pk_bf16_f32 v170, v80, v81
	v_cvt_pk_bf16_f32 v171, v82, v83
	v_cvt_pk_bf16_f32 v172, v84, v85
	v_mfma_f32_32x32x16_bf16 v[16:31], v[190:193], v[194:197], v[16:31]
	v_cvt_pk_bf16_f32 v173, v86, v87
	v_cvt_pk_bf16_f32 v178, v88, v89
	v_cvt_pk_bf16_f32 v179, v90, v91
	v_cvt_pk_bf16_f32 v180, v92, v93
	v_cvt_pk_bf16_f32 v181, v94, v95
	ds_read_b128 v[182:185], v168 offset:27712
	ds_read_b128 v[186:189], v168 offset:27728
	ds_read_b128 v[190:193], v168 offset:32320
	ds_read_b128 v[194:197], v168 offset:32336
	s_waitcnt lgkmcnt(0)
	v_mfma_f32_32x32x16_bf16 v[48:63], v[128:131], v[170:173], v[48:63]
	v_add_f32_e32 v96, v97, v96
	v_add_f32_e32 v96, v98, v96
	v_add_f32_e32 v80, v81, v80
	v_add_f32_e32 v96, v99, v96
	v_mfma_f32_32x32x16_bf16 v[0:15], v[136:139], v[170:173], v[0:15]
	v_add_f32_e32 v80, v82, v80
	v_add_f32_e32 v96, v100, v96
	v_add_f32_e32 v80, v83, v80
	v_add_f32_e32 v96, v101, v96
	v_mfma_f32_32x32x16_bf16 v[48:63], v[132:135], v[178:181], v[48:63]
	v_add_f32_e32 v80, v84, v80
	v_add_f32_e32 v96, v102, v96
	v_add_f32_e32 v80, v85, v80
	v_add_f32_e32 v96, v103, v96
	v_mfma_f32_32x32x16_bf16 v[0:15], v[140:143], v[178:181], v[0:15]
	v_add_f32_e32 v80, v86, v80
	v_add_f32_e32 v96, v104, v96
	v_add_f32_e32 v80, v87, v80
	v_add_f32_e32 v96, v105, v96
	v_mfma_f32_32x32x16_bf16 v[32:47], v[182:185], v[170:173], v[32:47]
	v_add_f32_e32 v80, v88, v80
	v_add_f32_e32 v96, v106, v96
	v_add_f32_e32 v80, v89, v80
	v_add_f32_e32 v96, v107, v96
	v_mfma_f32_32x32x16_bf16 v[16:31], v[190:193], v[170:173], v[16:31]
	v_add_f32_e32 v80, v90, v80
	v_add_f32_e32 v96, v108, v96
	v_add_f32_e32 v80, v91, v80
	v_add_f32_e32 v96, v109, v96
	v_mfma_f32_32x32x16_bf16 v[32:47], v[186:189], v[178:181], v[32:47]
	v_add_f32_e32 v80, v92, v80
	v_add_f32_e32 v96, v110, v96
	v_add_f32_e32 v80, v93, v80
	v_add_f32_e32 v96, v111, v96
	v_mfma_f32_32x32x16_bf16 v[16:31], v[194:197], v[178:181], v[16:31]
	v_add_f32_e32 v80, v94, v80
	v_add_f32_e32 v96, v157, v96
	v_add_f32_e32 v80, v95, v80
	v_add_f32_e32 v157, v96, v80
	s_mov_b64 s[60:61], -1
	s_and_b64 vcc, exec, s[50:51]
	s_cbranch_vccz .LBB0_647
	s_waitcnt vmcnt(0) lgkmcnt(0)
	s_barrier
	s_mov_b64 s[60:61], 0

.LBB0_699:
	s_add_i32 s4, s44, 0x9000
	s_cmp_lg_u32 s44, 0x12000
	s_cselect_b32 s44, s4, 0
	s_add_i32 s4, s45, 1
	s_cmp_lg_u32 s45, 2
	s_cselect_b32 s45, s4, 0
	s_add_i32 s33, s33, 1
	s_add_u32 s40, s40, 0x80
	s_addc_u32 s41, s41, 0
	s_add_u32 s46, s46, 0x60000
	s_addc_u32 s47, s47, 0
	s_add_i32 s20, s20, 64
	s_cmpk_eq_i32 s20, 0x7c0
	s_cbranch_scc1 .LBB0_710

.LBB0_706:
	ds_read_b128 v[178:181], v168 offset:27648
	ds_read_b128 v[182:185], v168 offset:27664
	ds_read_b128 v[186:189], v168 offset:32256
	ds_read_b128 v[190:193], v168 offset:32272
	v_exp_f32_e32 v96, v96
	v_exp_f32_e32 v97, v97
	v_exp_f32_e32 v98, v98
	v_exp_f32_e32 v99, v99
	v_exp_f32_e32 v100, v100
	v_exp_f32_e32 v101, v101
	v_exp_f32_e32 v102, v102
	v_exp_f32_e32 v103, v103
	v_exp_f32_e32 v104, v104
	v_exp_f32_e32 v105, v105
	v_exp_f32_e32 v106, v106
	v_exp_f32_e32 v107, v107
	v_exp_f32_e32 v108, v108
	v_exp_f32_e32 v109, v109
	v_exp_f32_e32 v110, v110
	v_exp_f32_e32 v111, v111
	v_cvt_pk_bf16_f32 v170, v96, v97
	v_cvt_pk_bf16_f32 v171, v98, v99
	v_cvt_pk_bf16_f32 v172, v100, v101
	v_cvt_pk_bf16_f32 v173, v102, v103
	v_cvt_pk_bf16_f32 v194, v104, v105
	v_cvt_pk_bf16_f32 v195, v106, v107
	v_cvt_pk_bf16_f32 v196, v108, v109
	v_cvt_pk_bf16_f32 v197, v110, v111
	s_waitcnt lgkmcnt(0)
	v_mfma_f32_32x32x16_bf16 v[48:63], v[140:143], v[170:173], v[48:63]
	v_exp_f32_e32 v80, v80
	v_exp_f32_e32 v81, v81
	v_exp_f32_e32 v82, v82
	v_exp_f32_e32 v83, v83
	v_mfma_f32_32x32x16_bf16 v[0:15], v[136:139], v[170:173], v[0:15]
	v_mfma_f32_32x32x16_bf16 v[48:63], v[132:135], v[194:197], v[48:63]
	v_exp_f32_e32 v84, v84
	v_exp_f32_e32 v85, v85
	v_exp_f32_e32 v86, v86
	v_exp_f32_e32 v87, v87
	v_mfma_f32_32x32x16_bf16 v[0:15], v[128:131], v[194:197], v[0:15]
	ds_read_b128 v[128:131], v168 offset:18496
	ds_read_b128 v[132:135], v168 offset:18512
	ds_read_b128 v[136:139], v168 offset:23104
	ds_read_b128 v[140:143], v168 offset:23120
	v_mfma_f32_32x32x16_bf16 v[32:47], v[178:181], v[170:173], v[32:47]
	v_exp_f32_e32 v88, v88
	v_exp_f32_e32 v89, v89
	v_exp_f32_e32 v90, v90
	v_exp_f32_e32 v91, v91
	v_mfma_f32_32x32x16_bf16 v[16:31], v[186:189], v[170:173], v[16:31]
	v_mfma_f32_32x32x16_bf16 v[32:47], v[182:185], v[194:197], v[32:47]
	v_exp_f32_e32 v92, v92
	v_exp_f32_e32 v93, v93
	v_exp_f32_e32 v94, v94
	v_exp_f32_e32 v95, v95
	v_cvt_pk_bf16_f32 v170, v80, v81
	v_cvt_pk_bf16_f32 v171, v82, v83
	v_cvt_pk_bf16_f32 v172, v84, v85
	v_mfma_f32_32x32x16_bf16 v[16:31], v[190:193], v[194:197], v[16:31]
	v_cvt_pk_bf16_f32 v173, v86, v87
	v_cvt_pk_bf16_f32 v178, v88, v89
	v_cvt_pk_bf16_f32 v179, v90, v91
	v_cvt_pk_bf16_f32 v180, v92, v93
	v_cvt_pk_bf16_f32 v181, v94, v95
	ds_read_b128 v[182:185], v168 offset:27712
	ds_read_b128 v[186:189], v168 offset:27728
	ds_read_b128 v[190:193], v168 offset:32320
	ds_read_b128 v[194:197], v168 offset:32336
	s_waitcnt lgkmcnt(0)
	v_mfma_f32_32x32x16_bf16 v[48:63], v[128:131], v[170:173], v[48:63]
	v_add_f32_e32 v96, v97, v96
	v_add_f32_e32 v96, v98, v96
	v_add_f32_e32 v80, v81, v80
	v_add_f32_e32 v96, v99, v96
	v_mfma_f32_32x32x16_bf16 v[0:15], v[136:139], v[170:173], v[0:15]
	v_add_f32_e32 v80, v82, v80
	v_add_f32_e32 v96, v100, v96
	v_add_f32_e32 v80, v83, v80
	v_add_f32_e32 v96, v101, v96
	v_mfma_f32_32x32x16_bf16 v[48:63], v[132:135], v[178:181], v[48:63]
	v_add_f32_e32 v80, v84, v80
	v_add_f32_e32 v96, v102, v96
	v_add_f32_e32 v80, v85, v80
	v_add_f32_e32 v96, v103, v96
	v_mfma_f32_32x32x16_bf16 v[0:15], v[140:143], v[178:181], v[0:15]
	v_add_f32_e32 v80, v86, v80
	v_add_f32_e32 v96, v104, v96
	v_add_f32_e32 v80, v87, v80
	v_add_f32_e32 v96, v105, v96
	v_mfma_f32_32x32x16_bf16 v[32:47], v[182:185], v[170:173], v[32:47]
	v_add_f32_e32 v80, v88, v80
	v_add_f32_e32 v96, v106, v96
	v_add_f32_e32 v80, v89, v80
	v_add_f32_e32 v96, v107, v96
	v_mfma_f32_32x32x16_bf16 v[16:31], v[190:193], v[170:173], v[16:31]
	v_add_f32_e32 v80, v90, v80
	v_add_f32_e32 v96, v108, v96
	v_add_f32_e32 v80, v91, v80
	v_add_f32_e32 v96, v109, v96
	v_mfma_f32_32x32x16_bf16 v[32:47], v[186:189], v[178:181], v[32:47]
	v_add_f32_e32 v80, v92, v80
	v_add_f32_e32 v96, v110, v96
	v_add_f32_e32 v80, v93, v80
	v_add_f32_e32 v96, v111, v96
	v_mfma_f32_32x32x16_bf16 v[16:31], v[194:197], v[178:181], v[16:31]
	v_add_f32_e32 v80, v94, v80
	v_add_f32_e32 v96, v157, v96
	v_add_f32_e32 v80, v95, v80
	v_add_f32_e32 v157, v96, v80
	s_mov_b64 s[62:63], -1
	s_and_b64 vcc, exec, s[60:61]
	s_cbranch_vccz .LBB0_708
	s_waitcnt vmcnt(0) lgkmcnt(0)
	s_barrier
	s_mov_b64 s[62:63], 0
